# odd blocks start the three big GEMM phases a few microseconds late so the two halves tile epilogues (HBM bursts) no longer coincide
# speedup vs baseline: 1.0314x; 1.0016x over previous
; #define PG8_WAIT_V(n) asm volatile("s_waitcnt vmcnt(" #n ")" ::: "memory")
; template <class Epi>
; __device__ __forceinline__ void gemm_phase(LAS unsigned char* lds, const Gemm g, const StaticOrder& S, const Epi& E) {
;     const int tid = threadIdx.x, wid = __builtin_amdgcn_readfirstlane(tid >> 6), lane = tid & 63, wr = wid >> 2, wc = wid & 3, fr = lane & 15, fq = lane >> 4;
;     const int K = g.K, nt = K / BK;
;     unsigned voffA[2], voffB[2];
; #pragma unroll
;     for (int i = 0; i < 2; ++i) { int R, C; stage_rc(tid * 16 + i * 8192, R, C); const int Rb = Epi::PERM ? ((R & ~31) + perm32(R & 31)) : R;
;         voffA[i] = (unsigned)(R * g.lda + C) * 2u; voffB[i] = (unsigned)(Rb * g.ldb + C) * 2u; }
;     const size_t kstep = (size_t)(BK * 2);
;     const size_t hstepA = (size_t)HALF * g.lda * 2, hstepB = (size_t)HALF * g.ldb * 2;
;     const size_t tstepA = 2 * hstepA, tstepB = 2 * hstepB;
;     const unsigned ldsw = (unsigned)wid * 1024u;
;     const int aoff = lds_byte(wr * 64 + fr, fq * 8), boff = lds_byte(wc * 32 + fr, fq * 8);
;     ...
;     Unit cur, nxt; int ui = 0;
;     if (!S.next(0, cur)) return;
;     f32x4 acc[2][2][4][2];
; #pragma unroll
;     for (int a = 0; a < 2; ++a)
; #pragma unroll
;         for (int b = 0; b < 2; ++b)
; #pragma unroll
;             for (int m = 0; m < 4; ++m)
; #pragma unroll
;                 for (int n = 0; n < 2; ++n) acc[a][b][m][n] = (f32x4){0.f, 0.f, 0.f, 0.f};
;     bf16x8 At[4][2], B0[2][2], B1[2][2];
;     const char* cA = (const char*)g.A + (size_t)cur.pm * tstepA; const char* cB = (const char*)g.Bt + (size_t)cur.pn * tstepB;
;     PG8_STAGE(PG8_SB(0, 0), cB, voffB); PG8_STAGE(PG8_SA(0, 0), cA, voffA); PG8_STAGE(PG8_SB(0, 1), cB + hstepB, voffB); PG8_STAGE(PG8_SA(0, 1), cA + hstepA, voffA);
;     if (wr == 1) PG8_BAR;
;     PG8_WAIT_V(4); PG8_BAR;
;     PG8_STAGE(PG8_SB(1, 0), cB + kstep, voffB); PG8_STAGE(PG8_SA(1, 0), cA + kstep, voffA); PG8_STAGE(PG8_SB(1, 1), cB + hstepB + kstep, voffB);
;     PG8_WAIT_V(6); PG8_BAR;
; __global__ void __launch_bounds__(NTHREADS, 2) mega(Params p) {
;     ...
;     RUN(1, {
;         EpiZ e; e.zs = (u16*)(ws + O_ZS); e.zg = (u16*)(ws + O_ZG); e.qn = (u16*)p.out; e.kn = e.qn + (size_t)NTOK * RW; e.vt = e.kn + (size_t)NTOK * RW; e.gn = e.vt + (size_t)NTOK * RW;
;         run_gemm(lds, (const u16*)(ws + O_HN), (const u16*)(ws + O_W1T), NTOK, 8448, 2048, e); })
.LBB0_117:
	s_cmp_lt_i32 s58, 2
	s_cselect_b64 s[0:1], -1, 0
	s_cmp_gt_i32 s59, 1
	s_cselect_b64 s[4:5], -1, 0
	s_and_b64 s[0:1], s[0:1], s[4:5]
	s_andn2_b64 vcc, exec, s[0:1]
	s_cbranch_vccnz .LBB0_204
	s_bitcmp1_b32 s2, 0
	s_cbranch_scc0 .Lmy_stg1_skip
	s_sleep 100
.Lmy_stg1_skip:
	s_cmpk_gt_i32 s2, 0x107f
	v_readfirstlane_b32 s3, v254
	s_cbranch_scc1 .LBB0_150
	v_lshrrev_b32_e32 v0, 5, v254
	v_lshrrev_b32_e32 v2, 1, v254
	v_and_b32_e32 v0, 4, v0
	v_bfe_u32 v1, v254, 2, 2
	v_and_b32_e32 v11, 24, v2
	v_or3_b32 v0, v0, v1, v11
	v_lshlrev_b32_e32 v1, 4, v254
	v_add_u32_e32 v8, 0x2000, v1
	v_lshrrev_b32_e32 v2, 7, v8
	s_movk_i32 s0, 0xe0
	v_and_b32_e32 v4, 32, v254
	v_and_or_b32 v3, v2, s0, v0
	v_bitop3_b32 v9, v1, v4, 48 bitop3:0x6c
	v_and_b32_e32 v10, 64, v254
	v_bfe_u32 v12, v254, 2, 4
	s_movk_i32 s0, 0xf0
	v_or_b32_e32 v1, v9, v10
	v_and_or_b32 v2, v2, s0, v12
	s_add_u32 s72, s56, 0x3800000
	v_lshl_or_b32 v130, v2, 12, v1
	v_lshrrev_b32_e32 v2, 3, v254
	s_movk_i32 s0, 0x60
	s_addc_u32 s73, s57, 0
	v_and_or_b32 v0, v2, s0, v0
	s_movk_i32 s0, 0x70
	s_ashr_i32 s75, s2, 31
	v_lshl_or_b32 v132, v0, 12, v1
	v_and_or_b32 v0, v2, s0, v12
	s_lshr_b32 s0, s75, 29
	s_add_i32 s0, s2, s0
	s_lshr_b32 s5, s3, 6
	s_ashr_i32 s1, s0, 3
	s_and_b32 s0, s0, -8
	s_lshr_b32 s26, s3, 8
	s_lshl_b32 s74, s5, 10
	s_sub_i32 s0, s2, s0
	s_cmp_lt_i32 s0, 0
	s_movk_i32 s76, 0x211
	s_cselect_b32 s4, s76, 0x210
	s_mul_i32 s0, s4, s0
	s_add_i32 s0, s0, s1
	s_mul_hi_i32 s1, s0, 0x3e0f83e1
	s_lshr_b32 s4, s1, 31
	s_ashr_i32 s1, s1, 6
	s_add_i32 s1, s1, s4
	s_lshl_b32 s6, s1, 3
	s_mulk_i32 s1, 0x108
	s_sub_i32 s0, s0, s1
	s_sext_i32_i16 s1, s0
	s_bfe_u32 s1, s1, 0x3001c
	s_add_i32 s1, s0, s1
	s_sext_i32_i16 s4, s1
	s_and_b32 s1, s1, 0xfff8
	s_sub_i32 s0, s0, s1
	s_sext_i32_i16 s0, s0
	s_lshr_b32 s4, s4, 3
	s_add_i32 s64, s6, s0
	s_ashr_i32 s65, s64, 31
	s_bfe_i64 s[6:7], s[4:5], 0x100000
	s_lshl_b64 s[0:1], s[64:65], 20
	s_lshl_b64 s[6:7], s[6:7], 20
	s_add_u32 s68, s56, s6
	s_addc_u32 s69, s57, s7
	s_add_i32 s77, s74, 0
	s_add_i32 m0, s77, 0x10000
	v_lshl_or_b32 v128, v3, 12, v1
	global_load_lds_dwordx4 v132, s[68:69]
	s_add_i32 m0, s77, 0x12000
	s_add_u32 s66, s72, s0
	v_lshl_or_b32 v134, v0, 12, v1
	global_load_lds_dwordx4 v128, s[68:69]
	s_addc_u32 s67, s73, s1
	s_mov_b32 m0, s77
	s_add_i32 s78, s77, 0x2000
	global_load_lds_dwordx4 v134, s[66:67]
	s_mov_b32 m0, s78
	s_add_u32 s0, s68, 0x80000
	global_load_lds_dwordx4 v130, s[66:67]
	s_addc_u32 s1, s69, 0
	s_add_i32 m0, s77, 0x14000
	v_mov_b32_e32 v137, 0
	global_load_lds_dwordx4 v132, s[0:1]
	s_add_i32 m0, s77, 0x16000
	v_mov_b32_e32 v133, v137
	global_load_lds_dwordx4 v128, s[0:1]
	s_add_u32 s0, s66, 0x80000
	s_addc_u32 s1, s67, 0
	s_add_i32 s79, s77, 0x4000
	s_mov_b32 m0, s79
	s_add_i32 s80, s77, 0x6000
	global_load_lds_dwordx4 v134, s[0:1]
	s_mov_b32 m0, s80
	v_mov_b32_e32 v129, v137
	global_load_lds_dwordx4 v130, s[0:1]
	v_mov_b32_e32 v135, v137
	v_mov_b32_e32 v131, v137
	s_mov_b32 s81, 0
	v_lshl_add_u64 v[6:7], s[68:69], 0, v[132:133]
	v_lshl_add_u64 v[4:5], s[68:69], 0, v[128:129]
	v_lshl_add_u64 v[2:3], s[66:67], 0, v[134:135]
	s_cmp_lg_u32 s26, 1
	v_lshl_add_u64 v[0:1], s[66:67], 0, v[130:131]
	s_cbranch_scc1 .LBB0_121
	s_barrier

; #define RUN(n, ...) if (PH_ON(n)) { __VA_ARGS__ if (PROBE_PH == (n)) { __syncthreads(); __VA_ARGS__ } PH_END(n); }
; template <class Epi>
; __device__ __forceinline__ void gemm_phase(LAS unsigned char* lds, const Gemm g, const StaticOrder& S, const Epi& E) {
;     const int tid = threadIdx.x, wid = __builtin_amdgcn_readfirstlane(tid >> 6), lane = tid & 63, wr = wid >> 2, wc = wid & 3, fr = lane & 15, fq = lane >> 4;
;     const int K = g.K, nt = K / BK;
;     unsigned voffA[2], voffB[2];
; #pragma unroll
;     for (int i = 0; i < 2; ++i) { int R, C; stage_rc(tid * 16 + i * 8192, R, C); const int Rb = Epi::PERM ? ((R & ~31) + perm32(R & 31)) : R;
;         voffA[i] = (unsigned)(R * g.lda + C) * 2u; voffB[i] = (unsigned)(Rb * g.ldb + C) * 2u; }
;     const size_t kstep = (size_t)(BK * 2);
;     const size_t hstepA = (size_t)HALF * g.lda * 2, hstepB = (size_t)HALF * g.ldb * 2;
;     const size_t tstepA = 2 * hstepA, tstepB = 2 * hstepB;
;     const unsigned ldsw = (unsigned)wid * 1024u;
;     const int aoff = lds_byte(wr * 64 + fr, fq * 8), boff = lds_byte(wc * 32 + fr, fq * 8);
; __global__ void __launch_bounds__(NTHREADS, 2) mega(Params p) {
;     ...
;     RUN(12, {
;         EpiH e; e.X = p.x; e.H = p.out;
;         run_gemm(lds, (const u16*)(ws + O_HN), (const u16*)(ws + O_W2T), NTOK, 2048, 2048, e);
.LBB0_1073:
	s_cmp_lt_i32 s58, 13
	s_cselect_b64 s[0:1], -1, 0
	s_cmp_gt_i32 s59, 12
	s_cselect_b64 s[4:5], -1, 0
	s_and_b64 s[0:1], s[0:1], s[4:5]
	s_andn2_b64 vcc, exec, s[0:1]
	s_cbranch_vccnz .LBB0_1166
	s_bitcmp1_b32 s2, 0
	s_cbranch_scc0 .Lmy_stg12_skip
	s_sleep 127
	s_sleep 127
	s_sleep 127
.Lmy_stg12_skip:
	s_waitcnt vmcnt(10)
	v_lshlrev_b32_e32 v0, 4, v254
	v_and_b32_e32 v1, 32, v254
	s_waitcnt vmcnt(2)
	v_bfe_u32 v10, v254, 2, 4
	v_bitop3_b32 v8, v0, v1, 48 bitop3:0x6c
	v_lshrrev_b32_e32 v146, 3, v254
	s_movk_i32 s0, 0x70
	v_add_u32_e32 v11, 0x2000, v0
	v_lshlrev_b32_e32 v0, 6, v254
	v_and_b32_e32 v9, 64, v254
	v_and_or_b32 v149, v146, s0, v10
	v_lshrrev_b32_e32 v147, 7, v11
	s_movk_i32 s0, 0xf0
	v_and_b32_e32 v142, 0x3c0, v0
	v_lshlrev_b32_e32 v0, 2, v254
	s_cmpk_lt_i32 s2, 0x400
	v_readfirstlane_b32 s3, v254
	v_or_b32_e32 v145, v8, v9
	v_and_or_b32 v150, v147, s0, v10
	v_and_b32_e32 v143, 15, v254
	s_cselect_b64 s[0:1], -1, 0
	s_cmpk_gt_i32 s2, 0x3ff
	v_and_b32_e32 v144, 32, v0
	s_cbranch_scc1 .LBB0_1094
	s_waitcnt lgkmcnt(0)
	s_ashr_i32 s40, s2, 31
	s_lshr_b32 s4, s40, 29
	s_add_i32 s6, s2, s4
	s_and_b32 s4, s6, -8
	s_sub_i32 s8, s2, s4
	s_cmp_gt_i32 s8, -1
	s_cbranch_scc0 .LBB0_1077
	s_lshl_b32 s7, s8, 7
	s_cbranch_execz .LBB0_1078
	s_branch .LBB0_1079

; #define RUN(n, ...) if (PH_ON(n)) { __VA_ARGS__ if (PROBE_PH == (n)) { __syncthreads(); __VA_ARGS__ } PH_END(n); }
;     __device__ bool next(int i, Unit& u) const {
;         const long L = (long)i * G + c; if (L >= nwg) return false;
;         int wgid = (int)L; { const int q = nwg / NXCD, r = nwg % NXCD, xcd = wgid % NXCD, off = wgid / NXCD; wgid = (xcd < r ? xcd * (q + 1) : r * (q + 1) + (xcd - r) * q) + off; }
;         const int nig = WGM * nN, gid = wgid / nig, fm = gid * WGM, gsz = (nM - fm) < WGM ? (nM - fm) : WGM;
;         u.pm = fm + ((wgid % nig) % gsz); u.pn = (wgid % nig) / gsz; return true;
; __global__ void __launch_bounds__(NTHREADS, 2) mega(Params p) {
;     ...
;     RUN(14, {
;         EpiGate e; e.H = p.out; e.PP = (const u16*)(ws + O_R);
;         run_gemm(lds, (const u16*)(ws + O_HN), (const u16*)(ws + O_W3T), NTOK, 2048, 2048, e); })
.LBB0_1224:
	s_cmp_lt_i32 s58, 15
	s_cselect_b64 s[0:1], -1, 0
	s_cmp_gt_i32 s59, 14
	s_cselect_b64 s[4:5], -1, 0
	s_and_b64 s[0:1], s[0:1], s[4:5]
	s_andn2_b64 vcc, exec, s[0:1]
	s_cbranch_vccnz .LBB0_1299
	s_bitcmp1_b32 s2, 0
	s_cbranch_scc0 .Lmy_stg14_skip
	s_sleep 127
	s_sleep 127
	s_sleep 127
.Lmy_stg14_skip:
	s_cmpk_gt_i32 s2, 0x3ff
	v_readfirstlane_b32 s3, v254
	s_cbranch_scc1 .LBB0_1245
	s_waitcnt lgkmcnt(0)
	s_ashr_i32 s38, s2, 31
	s_lshr_b32 s0, s38, 29
	s_add_i32 s6, s2, s0
	s_and_b32 s0, s6, -8
	s_sub_i32 s5, s2, s0
	s_cmp_gt_i32 s5, -1
	s_cbranch_scc0 .LBB0_1228
	s_lshl_b32 s4, s5, 7
	s_ashr_i32 s0, s6, 3
	s_cbranch_execz .LBB0_1229
	s_branch .LBB0_1230
